# P3 attention epilogue: hoisted wide Z/gain loads, no per-store waits, dwordx4 stores via permlane32_swap
# speedup vs baseline: 1.0263x; 1.0263x over previous
.LBB0_357:
	v_readlane_b32 s0, v244, 23
	v_readlane_b32 s16, v244, 29
	v_readlane_b32 s17, v244, 30
	s_cmp_eq_u32 s0, 0
	s_cbranch_scc1 .Lepi_noload
	v_readlane_b32 s0, v244, 32
	v_and_or_b32 v65, v145, 31, s34
	v_or_b32_e32 v65, s2, v65
	v_lshlrev_b32_e32 v66, 4, v144
	v_or_b32_e32 v108, s0, v65
	v_mov_b32_e32 v109, 0
	v_readlane_b32 s0, v245, 63
	v_readlane_b32 s1, v244, 0
	v_readlane_b32 s24, v245, 40
	v_readlane_b32 s25, v245, 41
	v_lshlrev_b64 v[108:109], 11, v[108:109]
	v_mov_b32_e32 v67, 0
	v_lshl_or_b32 v108, s95, 8, v108
	v_lshl_add_u64 v[110:111], s[16:17], 0, v[108:109]
	v_lshl_add_u64 v[108:109], s[0:1], 0, v[108:109]
	v_lshl_add_u64 v[110:111], v[110:111], 0, v[66:67]
	v_lshl_add_u64 v[108:109], v[108:109], 0, v[66:67]
	global_load_dwordx4 v[148:151], v[108:109], off offset:0
	global_load_dwordx4 v[152:155], v[108:109], off offset:32
	global_load_dwordx4 v[156:159], v[108:109], off offset:64
	global_load_dwordx4 v[160:163], v[108:109], off offset:96
	global_load_dwordx4 v[164:167], v[108:109], off offset:128
	global_load_dwordx4 v[168:171], v[108:109], off offset:160
	global_load_dwordx4 v[172:175], v[108:109], off offset:192
	global_load_dwordx4 v[176:179], v[108:109], off offset:224
	global_load_dwordx4 v[180:183], v66, s[24:25] offset:0
	global_load_dwordx4 v[184:187], v66, s[24:25] offset:32
	global_load_dwordx4 v[188:191], v66, s[24:25] offset:64
	global_load_dwordx4 v[192:195], v66, s[24:25] offset:96
	global_load_dwordx4 v[196:199], v66, s[24:25] offset:128
	global_load_dwordx4 v[200:203], v66, s[24:25] offset:160
	global_load_dwordx4 v[212:215], v66, s[24:25] offset:192
	global_load_dwordx4 v[216:219], v66, s[24:25] offset:224
	global_load_dwordx4 v[220:223], v66, s[24:25] offset:256
	global_load_dwordx4 v[232:235], v66, s[24:25] offset:288
	global_load_dwordx4 v[236:239], v66, s[24:25] offset:320
	global_load_dwordx4 v[240:243], v66, s[24:25] offset:352
	global_load_dwordx4 v[132:135], v66, s[24:25] offset:384
	global_load_dwordx4 v[136:139], v66, s[24:25] offset:416
	global_load_dwordx4 v[140:143], v66, s[24:25] offset:448
	global_load_dwordx4 v[104:107], v66, s[24:25] offset:480

.LBB0_359:
	v_readlane_b32 s0, v244, 23
	s_waitcnt lgkmcnt(0)
	s_barrier
	v_readlane_b32 s1, v244, 24
	v_readlane_b32 s56, v244, 29
	s_andn2_b64 vcc, exec, s[0:1]
	v_readlane_b32 s57, v244, 30
	s_cbranch_vccnz .LBB0_302
	v_mov_b32_e32 v69, 0
	v_mov_b32_e32 v70, 0
	ds_read2st64_b32 v[72:73], v112 offset0:64 offset1:65
	ds_read2st64_b32 v[74:75], v112 offset0:66 offset1:67
	ds_read2st64_b32 v[76:77], v112 offset0:68 offset1:69
	ds_read2st64_b32 v[78:79], v112 offset0:70 offset1:71
	ds_read2st64_b32 v[80:81], v112 offset0:72 offset1:73
	ds_read2st64_b32 v[82:83], v112 offset0:74 offset1:75
	ds_read2st64_b32 v[84:85], v112 offset0:76 offset1:77
	ds_read2st64_b32 v[86:87], v112 offset0:78 offset1:79
	ds_read2st64_b32 v[88:89], v112 offset0:80 offset1:81
	ds_read2st64_b32 v[90:91], v112 offset0:82 offset1:83
	ds_read2st64_b32 v[92:93], v112 offset0:84 offset1:85
	ds_read2st64_b32 v[94:95], v112 offset0:86 offset1:87
	s_waitcnt lgkmcnt(8)
	v_mul_f32_e32 v68, v206, v72
	v_fma_f32 v48, v48, v64, -v68
	v_fmac_f32_e32 v69, v48, v48
	v_mul_f32_e32 v68, v206, v73
	v_fma_f32 v49, v49, v64, -v68
	v_fmac_f32_e32 v70, v49, v49
	v_mul_f32_e32 v68, v206, v74
	v_fma_f32 v50, v50, v64, -v68
	v_fmac_f32_e32 v69, v50, v50
	v_mul_f32_e32 v68, v206, v75
	v_fma_f32 v51, v51, v64, -v68
	v_fmac_f32_e32 v70, v51, v51
	v_mul_f32_e32 v68, v206, v76
	v_fma_f32 v52, v52, v64, -v68
	v_fmac_f32_e32 v69, v52, v52
	v_mul_f32_e32 v68, v206, v77
	v_fma_f32 v53, v53, v64, -v68
	v_fmac_f32_e32 v70, v53, v53
	v_mul_f32_e32 v68, v206, v78
	v_fma_f32 v54, v54, v64, -v68
	v_fmac_f32_e32 v69, v54, v54
	v_mul_f32_e32 v68, v206, v79
	v_fma_f32 v55, v55, v64, -v68
	v_fmac_f32_e32 v70, v55, v55
	ds_read2st64_b32 v[72:73], v112 offset0:88 offset1:89
	ds_read2st64_b32 v[74:75], v112 offset0:90 offset1:91
	ds_read2st64_b32 v[76:77], v112 offset0:92 offset1:93
	ds_read2st64_b32 v[78:79], v112 offset0:94 offset1:95
	s_waitcnt lgkmcnt(8)
	v_mul_f32_e32 v68, v206, v80
	v_fma_f32 v56, v56, v64, -v68
	v_fmac_f32_e32 v69, v56, v56
	v_mul_f32_e32 v68, v206, v81
	v_fma_f32 v57, v57, v64, -v68
	v_fmac_f32_e32 v70, v57, v57
	v_mul_f32_e32 v68, v206, v82
	v_fma_f32 v58, v58, v64, -v68
	v_fmac_f32_e32 v69, v58, v58
	v_mul_f32_e32 v68, v206, v83
	v_fma_f32 v59, v59, v64, -v68
	v_fmac_f32_e32 v70, v59, v59
	v_mul_f32_e32 v68, v206, v84
	v_fma_f32 v60, v60, v64, -v68
	v_fmac_f32_e32 v69, v60, v60
	v_mul_f32_e32 v68, v206, v85
	v_fma_f32 v61, v61, v64, -v68
	v_fmac_f32_e32 v70, v61, v61
	v_mul_f32_e32 v68, v206, v86
	v_fma_f32 v62, v62, v64, -v68
	v_fmac_f32_e32 v69, v62, v62
	v_mul_f32_e32 v68, v206, v87
	v_fma_f32 v63, v63, v64, -v68
	v_fmac_f32_e32 v70, v63, v63
	ds_read2st64_b32 v[80:81], v112 offset0:96 offset1:97
	ds_read2st64_b32 v[82:83], v112 offset0:98 offset1:99
	ds_read2st64_b32 v[84:85], v112 offset0:100 offset1:101
	ds_read2st64_b32 v[86:87], v112 offset0:102 offset1:103
	s_waitcnt lgkmcnt(8)
	v_mul_f32_e32 v68, v206, v88
	v_fma_f32 v32, v32, v64, -v68
	v_fmac_f32_e32 v69, v32, v32
	v_mul_f32_e32 v68, v206, v89
	v_fma_f32 v33, v33, v64, -v68
	v_fmac_f32_e32 v70, v33, v33
	v_mul_f32_e32 v68, v206, v90
	v_fma_f32 v34, v34, v64, -v68
	v_fmac_f32_e32 v69, v34, v34
	v_mul_f32_e32 v68, v206, v91
	v_fma_f32 v35, v35, v64, -v68
	v_fmac_f32_e32 v70, v35, v35
	v_mul_f32_e32 v68, v206, v92
	v_fma_f32 v36, v36, v64, -v68
	v_fmac_f32_e32 v69, v36, v36
	v_mul_f32_e32 v68, v206, v93
	v_fma_f32 v37, v37, v64, -v68
	v_fmac_f32_e32 v70, v37, v37
	v_mul_f32_e32 v68, v206, v94
	v_fma_f32 v38, v38, v64, -v68
	v_fmac_f32_e32 v69, v38, v38
	v_mul_f32_e32 v68, v206, v95
	v_fma_f32 v39, v39, v64, -v68
	v_fmac_f32_e32 v70, v39, v39
	ds_read2st64_b32 v[88:89], v112 offset0:104 offset1:105
	ds_read2st64_b32 v[90:91], v112 offset0:106 offset1:107
	ds_read2st64_b32 v[92:93], v112 offset0:108 offset1:109
	ds_read2st64_b32 v[94:95], v112 offset0:110 offset1:111
	s_waitcnt lgkmcnt(8)
	v_mul_f32_e32 v68, v206, v72
	v_fma_f32 v40, v40, v64, -v68
	v_fmac_f32_e32 v69, v40, v40
	v_mul_f32_e32 v68, v206, v73
	v_fma_f32 v41, v41, v64, -v68
	v_fmac_f32_e32 v70, v41, v41
	v_mul_f32_e32 v68, v206, v74
	v_fma_f32 v42, v42, v64, -v68
	v_fmac_f32_e32 v69, v42, v42
	v_mul_f32_e32 v68, v206, v75
	v_fma_f32 v43, v43, v64, -v68
	v_fmac_f32_e32 v70, v43, v43
	v_mul_f32_e32 v68, v206, v76
	v_fma_f32 v44, v44, v64, -v68
	v_fmac_f32_e32 v69, v44, v44
	v_mul_f32_e32 v68, v206, v77
	v_fma_f32 v45, v45, v64, -v68
	v_fmac_f32_e32 v70, v45, v45
	v_mul_f32_e32 v68, v206, v78
	v_fma_f32 v46, v46, v64, -v68
	v_fmac_f32_e32 v69, v46, v46
	v_mul_f32_e32 v68, v206, v79
	v_fma_f32 v47, v47, v64, -v68
	v_fmac_f32_e32 v70, v47, v47
	ds_read2st64_b32 v[72:73], v112 offset0:112 offset1:113
	ds_read2st64_b32 v[74:75], v112 offset0:114 offset1:115
	ds_read2st64_b32 v[76:77], v112 offset0:116 offset1:117
	ds_read2st64_b32 v[78:79], v112 offset0:118 offset1:119
	s_waitcnt lgkmcnt(8)
	v_mul_f32_e32 v68, v206, v80
	v_fma_f32 v16, v16, v64, -v68
	v_fmac_f32_e32 v69, v16, v16
	v_mul_f32_e32 v68, v206, v81
	v_fma_f32 v17, v17, v64, -v68
	v_fmac_f32_e32 v70, v17, v17
	v_mul_f32_e32 v68, v206, v82
	v_fma_f32 v18, v18, v64, -v68
	v_fmac_f32_e32 v69, v18, v18
	v_mul_f32_e32 v68, v206, v83
	v_fma_f32 v19, v19, v64, -v68
	v_fmac_f32_e32 v70, v19, v19
	v_mul_f32_e32 v68, v206, v84
	v_fma_f32 v20, v20, v64, -v68
	v_fmac_f32_e32 v69, v20, v20
	v_mul_f32_e32 v68, v206, v85
	v_fma_f32 v21, v21, v64, -v68
	v_fmac_f32_e32 v70, v21, v21
	v_mul_f32_e32 v68, v206, v86
	v_fma_f32 v22, v22, v64, -v68
	v_fmac_f32_e32 v69, v22, v22
	v_mul_f32_e32 v68, v206, v87
	v_fma_f32 v23, v23, v64, -v68
	v_fmac_f32_e32 v70, v23, v23
	ds_read2st64_b32 v[80:81], v112 offset0:120 offset1:121
	ds_read2st64_b32 v[82:83], v112 offset0:122 offset1:123
	ds_read2st64_b32 v[84:85], v112 offset0:124 offset1:125
	ds_read2st64_b32 v[86:87], v112 offset0:126 offset1:127
	s_waitcnt lgkmcnt(8)
	v_mul_f32_e32 v68, v206, v88
	v_fma_f32 v24, v24, v64, -v68
	v_fmac_f32_e32 v69, v24, v24
	v_mul_f32_e32 v68, v206, v89
	v_fma_f32 v25, v25, v64, -v68
	v_fmac_f32_e32 v70, v25, v25
	v_mul_f32_e32 v68, v206, v90
	v_fma_f32 v26, v26, v64, -v68
	v_fmac_f32_e32 v69, v26, v26
	v_mul_f32_e32 v68, v206, v91
	v_fma_f32 v27, v27, v64, -v68
	v_fmac_f32_e32 v70, v27, v27
	v_mul_f32_e32 v68, v206, v92
	v_fma_f32 v28, v28, v64, -v68
	v_fmac_f32_e32 v69, v28, v28
	v_mul_f32_e32 v68, v206, v93
	v_fma_f32 v29, v29, v64, -v68
	v_fmac_f32_e32 v70, v29, v29
	v_mul_f32_e32 v68, v206, v94
	v_fma_f32 v30, v30, v64, -v68
	v_fmac_f32_e32 v69, v30, v30
	v_mul_f32_e32 v68, v206, v95
	v_fma_f32 v31, v31, v64, -v68
	v_fmac_f32_e32 v70, v31, v31
	s_waitcnt lgkmcnt(4)
	v_mul_f32_e32 v68, v206, v72
	v_fma_f32 v0, v0, v64, -v68
	v_fmac_f32_e32 v69, v0, v0
	v_mul_f32_e32 v68, v206, v73
	v_fma_f32 v1, v1, v64, -v68
	v_fmac_f32_e32 v70, v1, v1
	v_mul_f32_e32 v68, v206, v74
	v_fma_f32 v2, v2, v64, -v68
	v_fmac_f32_e32 v69, v2, v2
	v_mul_f32_e32 v68, v206, v75
	v_fma_f32 v3, v3, v64, -v68
	v_fmac_f32_e32 v70, v3, v3
	v_mul_f32_e32 v68, v206, v76
	v_fma_f32 v4, v4, v64, -v68
	v_fmac_f32_e32 v69, v4, v4
	v_mul_f32_e32 v68, v206, v77
	v_fma_f32 v5, v5, v64, -v68
	v_fmac_f32_e32 v70, v5, v5
	v_mul_f32_e32 v68, v206, v78
	v_fma_f32 v6, v6, v64, -v68
	v_fmac_f32_e32 v69, v6, v6
	v_mul_f32_e32 v68, v206, v79
	v_fma_f32 v7, v7, v64, -v68
	v_fmac_f32_e32 v70, v7, v7
	s_waitcnt lgkmcnt(0)
	v_mul_f32_e32 v68, v206, v80
	v_fma_f32 v8, v8, v64, -v68
	v_fmac_f32_e32 v69, v8, v8
	v_mul_f32_e32 v68, v206, v81
	v_fma_f32 v9, v9, v64, -v68
	v_fmac_f32_e32 v70, v9, v9
	v_mul_f32_e32 v68, v206, v82
	v_fma_f32 v10, v10, v64, -v68
	v_fmac_f32_e32 v69, v10, v10
	v_mul_f32_e32 v68, v206, v83
	v_fma_f32 v11, v11, v64, -v68
	v_fmac_f32_e32 v70, v11, v11
	v_mul_f32_e32 v68, v206, v84
	v_fma_f32 v12, v12, v64, -v68
	v_fmac_f32_e32 v69, v12, v12
	v_mul_f32_e32 v68, v206, v85
	v_fma_f32 v13, v13, v64, -v68
	v_fmac_f32_e32 v70, v13, v13
	v_mul_f32_e32 v68, v206, v86
	v_fma_f32 v14, v14, v64, -v68
	v_fmac_f32_e32 v69, v14, v14
	v_mul_f32_e32 v68, v206, v87
	v_fma_f32 v15, v15, v64, -v68
	v_fmac_f32_e32 v70, v15, v15
	v_add_f32_e32 v69, v69, v70
	s_nop 0
	v_mov_b32_e32 v70, v69
	s_nop 1
	v_permlane32_swap_b32_e32 v69, v70
	s_nop 1
	v_add_f32_e32 v69, v69, v70
	v_fmamk_f32 v69, v69, 0x3c000000, v226
	v_rsq_f32_e32 v69, v69
	s_nop 0
	v_mul_f32_e32 v69, 0x3f4ccccd, v69
	s_waitcnt vmcnt(0)
	v_permlane32_swap_b32_e32 v148, v150
	v_permlane32_swap_b32_e32 v149, v151
	v_permlane32_swap_b32_e32 v152, v154
	v_permlane32_swap_b32_e32 v153, v155
	v_permlane32_swap_b32_e32 v156, v158
	v_permlane32_swap_b32_e32 v157, v159
	v_permlane32_swap_b32_e32 v160, v162
	v_permlane32_swap_b32_e32 v161, v163
	v_permlane32_swap_b32_e32 v164, v166
	v_permlane32_swap_b32_e32 v165, v167
	v_permlane32_swap_b32_e32 v168, v170
	v_permlane32_swap_b32_e32 v169, v171
	v_permlane32_swap_b32_e32 v172, v174
	v_permlane32_swap_b32_e32 v173, v175
	v_permlane32_swap_b32_e32 v176, v178
	v_permlane32_swap_b32_e32 v177, v179
	s_nop 1
	v_mul_f32_e32 v48, v48, v69
	v_mul_f32_e32 v49, v49, v69
	v_mul_f32_e32 v50, v50, v69
	v_mul_f32_e32 v51, v51, v69
	v_mul_f32_e32 v48, v180, v48
	v_mul_f32_e32 v49, v181, v49
	v_mul_f32_e32 v50, v182, v50
	v_mul_f32_e32 v51, v183, v51
	v_lshlrev_b32_e32 v64, 16, v148
	v_and_b32_e32 v65, 0xffff0000, v148
	v_lshlrev_b32_e32 v66, 16, v149
	v_and_b32_e32 v67, 0xffff0000, v149
	v_mul_f32_e32 v48, v48, v64
	v_mul_f32_e32 v49, v49, v65
	v_mul_f32_e32 v50, v50, v66
	v_mul_f32_e32 v51, v51, v67
	v_cvt_pk_bf16_f32 v72, v48, v49
	v_cvt_pk_bf16_f32 v73, v50, v51
	v_mul_f32_e32 v52, v52, v69
	v_mul_f32_e32 v53, v53, v69
	v_mul_f32_e32 v54, v54, v69
	v_mul_f32_e32 v55, v55, v69
	v_mul_f32_e32 v52, v184, v52
	v_mul_f32_e32 v53, v185, v53
	v_mul_f32_e32 v54, v186, v54
	v_mul_f32_e32 v55, v187, v55
	v_lshlrev_b32_e32 v64, 16, v150
	v_and_b32_e32 v65, 0xffff0000, v150
	v_lshlrev_b32_e32 v66, 16, v151
	v_and_b32_e32 v67, 0xffff0000, v151
	v_mul_f32_e32 v52, v52, v64
	v_mul_f32_e32 v53, v53, v65
	v_mul_f32_e32 v54, v54, v66
	v_mul_f32_e32 v55, v55, v67
	v_cvt_pk_bf16_f32 v74, v52, v53
	v_cvt_pk_bf16_f32 v75, v54, v55
	v_mul_f32_e32 v56, v56, v69
	v_mul_f32_e32 v57, v57, v69
	v_mul_f32_e32 v58, v58, v69
	v_mul_f32_e32 v59, v59, v69
	v_mul_f32_e32 v56, v188, v56
	v_mul_f32_e32 v57, v189, v57
	v_mul_f32_e32 v58, v190, v58
	v_mul_f32_e32 v59, v191, v59
	v_lshlrev_b32_e32 v64, 16, v152
	v_and_b32_e32 v65, 0xffff0000, v152
	v_lshlrev_b32_e32 v66, 16, v153
	v_and_b32_e32 v67, 0xffff0000, v153
	v_mul_f32_e32 v56, v56, v64
	v_mul_f32_e32 v57, v57, v65
	v_mul_f32_e32 v58, v58, v66
	v_mul_f32_e32 v59, v59, v67
	v_cvt_pk_bf16_f32 v76, v56, v57
	v_cvt_pk_bf16_f32 v77, v58, v59
	v_mul_f32_e32 v60, v60, v69
	v_mul_f32_e32 v61, v61, v69
	v_mul_f32_e32 v62, v62, v69
	v_mul_f32_e32 v63, v63, v69
	v_mul_f32_e32 v60, v192, v60
	v_mul_f32_e32 v61, v193, v61
	v_mul_f32_e32 v62, v194, v62
	v_mul_f32_e32 v63, v195, v63
	v_lshlrev_b32_e32 v64, 16, v154
	v_and_b32_e32 v65, 0xffff0000, v154
	v_lshlrev_b32_e32 v66, 16, v155
	v_and_b32_e32 v67, 0xffff0000, v155
	v_mul_f32_e32 v60, v60, v64
	v_mul_f32_e32 v61, v61, v65
	v_mul_f32_e32 v62, v62, v66
	v_mul_f32_e32 v63, v63, v67
	v_cvt_pk_bf16_f32 v78, v60, v61
	v_cvt_pk_bf16_f32 v79, v62, v63
	v_mul_f32_e32 v32, v32, v69
	v_mul_f32_e32 v33, v33, v69
	v_mul_f32_e32 v34, v34, v69
	v_mul_f32_e32 v35, v35, v69
	v_mul_f32_e32 v32, v196, v32
	v_mul_f32_e32 v33, v197, v33
	v_mul_f32_e32 v34, v198, v34
	v_mul_f32_e32 v35, v199, v35
	v_lshlrev_b32_e32 v64, 16, v156
	v_and_b32_e32 v65, 0xffff0000, v156
	v_lshlrev_b32_e32 v66, 16, v157
	v_and_b32_e32 v67, 0xffff0000, v157
	v_mul_f32_e32 v32, v32, v64
	v_mul_f32_e32 v33, v33, v65
	v_mul_f32_e32 v34, v34, v66
	v_mul_f32_e32 v35, v35, v67
	v_cvt_pk_bf16_f32 v80, v32, v33
	v_cvt_pk_bf16_f32 v81, v34, v35
	v_mul_f32_e32 v36, v36, v69
	v_mul_f32_e32 v37, v37, v69
	v_mul_f32_e32 v38, v38, v69
	v_mul_f32_e32 v39, v39, v69
	v_mul_f32_e32 v36, v200, v36
	v_mul_f32_e32 v37, v201, v37
	v_mul_f32_e32 v38, v202, v38
	v_mul_f32_e32 v39, v203, v39
	v_lshlrev_b32_e32 v64, 16, v158
	v_and_b32_e32 v65, 0xffff0000, v158
	v_lshlrev_b32_e32 v66, 16, v159
	v_and_b32_e32 v67, 0xffff0000, v159
	v_mul_f32_e32 v36, v36, v64
	v_mul_f32_e32 v37, v37, v65
	v_mul_f32_e32 v38, v38, v66
	v_mul_f32_e32 v39, v39, v67
	v_cvt_pk_bf16_f32 v82, v36, v37
	v_cvt_pk_bf16_f32 v83, v38, v39
	v_mul_f32_e32 v40, v40, v69
	v_mul_f32_e32 v41, v41, v69
	v_mul_f32_e32 v42, v42, v69
	v_mul_f32_e32 v43, v43, v69
	v_mul_f32_e32 v40, v212, v40
	v_mul_f32_e32 v41, v213, v41
	v_mul_f32_e32 v42, v214, v42
	v_mul_f32_e32 v43, v215, v43
	v_lshlrev_b32_e32 v64, 16, v160
	v_and_b32_e32 v65, 0xffff0000, v160
	v_lshlrev_b32_e32 v66, 16, v161
	v_and_b32_e32 v67, 0xffff0000, v161
	v_mul_f32_e32 v40, v40, v64
	v_mul_f32_e32 v41, v41, v65
	v_mul_f32_e32 v42, v42, v66
	v_mul_f32_e32 v43, v43, v67
	v_cvt_pk_bf16_f32 v84, v40, v41
	v_cvt_pk_bf16_f32 v85, v42, v43
	v_mul_f32_e32 v44, v44, v69
	v_mul_f32_e32 v45, v45, v69
	v_mul_f32_e32 v46, v46, v69
	v_mul_f32_e32 v47, v47, v69
	v_mul_f32_e32 v44, v216, v44
	v_mul_f32_e32 v45, v217, v45
	v_mul_f32_e32 v46, v218, v46
	v_mul_f32_e32 v47, v219, v47
	v_lshlrev_b32_e32 v64, 16, v162
	v_and_b32_e32 v65, 0xffff0000, v162
	v_lshlrev_b32_e32 v66, 16, v163
	v_and_b32_e32 v67, 0xffff0000, v163
	v_mul_f32_e32 v44, v44, v64
	v_mul_f32_e32 v45, v45, v65
	v_mul_f32_e32 v46, v46, v66
	v_mul_f32_e32 v47, v47, v67
	v_cvt_pk_bf16_f32 v86, v44, v45
	v_cvt_pk_bf16_f32 v87, v46, v47
	v_mul_f32_e32 v16, v16, v69
	v_mul_f32_e32 v17, v17, v69
	v_mul_f32_e32 v18, v18, v69
	v_mul_f32_e32 v19, v19, v69
	v_mul_f32_e32 v16, v220, v16
	v_mul_f32_e32 v17, v221, v17
	v_mul_f32_e32 v18, v222, v18
	v_mul_f32_e32 v19, v223, v19
	v_lshlrev_b32_e32 v64, 16, v164
	v_and_b32_e32 v65, 0xffff0000, v164
	v_lshlrev_b32_e32 v66, 16, v165
	v_and_b32_e32 v67, 0xffff0000, v165
	v_mul_f32_e32 v16, v16, v64
	v_mul_f32_e32 v17, v17, v65
	v_mul_f32_e32 v18, v18, v66
	v_mul_f32_e32 v19, v19, v67
	v_cvt_pk_bf16_f32 v88, v16, v17
	v_cvt_pk_bf16_f32 v89, v18, v19
	v_mul_f32_e32 v20, v20, v69
	v_mul_f32_e32 v21, v21, v69
	v_mul_f32_e32 v22, v22, v69
	v_mul_f32_e32 v23, v23, v69
	v_mul_f32_e32 v20, v232, v20
	v_mul_f32_e32 v21, v233, v21
	v_mul_f32_e32 v22, v234, v22
	v_mul_f32_e32 v23, v235, v23
	v_lshlrev_b32_e32 v64, 16, v166
	v_and_b32_e32 v65, 0xffff0000, v166
	v_lshlrev_b32_e32 v66, 16, v167
	v_and_b32_e32 v67, 0xffff0000, v167
	v_mul_f32_e32 v20, v20, v64
	v_mul_f32_e32 v21, v21, v65
	v_mul_f32_e32 v22, v22, v66
	v_mul_f32_e32 v23, v23, v67
	v_cvt_pk_bf16_f32 v90, v20, v21
	v_cvt_pk_bf16_f32 v91, v22, v23
	v_mul_f32_e32 v24, v24, v69
	v_mul_f32_e32 v25, v25, v69
	v_mul_f32_e32 v26, v26, v69
	v_mul_f32_e32 v27, v27, v69
	v_mul_f32_e32 v24, v236, v24
	v_mul_f32_e32 v25, v237, v25
	v_mul_f32_e32 v26, v238, v26
	v_mul_f32_e32 v27, v239, v27
	v_lshlrev_b32_e32 v64, 16, v168
	v_and_b32_e32 v65, 0xffff0000, v168
	v_lshlrev_b32_e32 v66, 16, v169
	v_and_b32_e32 v67, 0xffff0000, v169
	v_mul_f32_e32 v24, v24, v64
	v_mul_f32_e32 v25, v25, v65
	v_mul_f32_e32 v26, v26, v66
	v_mul_f32_e32 v27, v27, v67
	v_cvt_pk_bf16_f32 v92, v24, v25
	v_cvt_pk_bf16_f32 v93, v26, v27
	v_mul_f32_e32 v28, v28, v69
	v_mul_f32_e32 v29, v29, v69
	v_mul_f32_e32 v30, v30, v69
	v_mul_f32_e32 v31, v31, v69
	v_mul_f32_e32 v28, v240, v28
	v_mul_f32_e32 v29, v241, v29
	v_mul_f32_e32 v30, v242, v30
	v_mul_f32_e32 v31, v243, v31
	v_lshlrev_b32_e32 v64, 16, v170
	v_and_b32_e32 v65, 0xffff0000, v170
	v_lshlrev_b32_e32 v66, 16, v171
	v_and_b32_e32 v67, 0xffff0000, v171
	v_mul_f32_e32 v28, v28, v64
	v_mul_f32_e32 v29, v29, v65
	v_mul_f32_e32 v30, v30, v66
	v_mul_f32_e32 v31, v31, v67
	v_cvt_pk_bf16_f32 v94, v28, v29
	v_cvt_pk_bf16_f32 v95, v30, v31
	v_mul_f32_e32 v0, v0, v69
	v_mul_f32_e32 v1, v1, v69
	v_mul_f32_e32 v2, v2, v69
	v_mul_f32_e32 v3, v3, v69
	v_mul_f32_e32 v0, v132, v0
	v_mul_f32_e32 v1, v133, v1
	v_mul_f32_e32 v2, v134, v2
	v_mul_f32_e32 v3, v135, v3
	v_lshlrev_b32_e32 v64, 16, v172
	v_and_b32_e32 v65, 0xffff0000, v172
	v_lshlrev_b32_e32 v66, 16, v173
	v_and_b32_e32 v67, 0xffff0000, v173
	v_mul_f32_e32 v0, v0, v64
	v_mul_f32_e32 v1, v1, v65
	v_mul_f32_e32 v2, v2, v66
	v_mul_f32_e32 v3, v3, v67
	v_cvt_pk_bf16_f32 v96, v0, v1
	v_cvt_pk_bf16_f32 v97, v2, v3
	v_mul_f32_e32 v4, v4, v69
	v_mul_f32_e32 v5, v5, v69
	v_mul_f32_e32 v6, v6, v69
	v_mul_f32_e32 v7, v7, v69
	v_mul_f32_e32 v4, v136, v4
	v_mul_f32_e32 v5, v137, v5
	v_mul_f32_e32 v6, v138, v6
	v_mul_f32_e32 v7, v139, v7
	v_lshlrev_b32_e32 v64, 16, v174
	v_and_b32_e32 v65, 0xffff0000, v174
	v_lshlrev_b32_e32 v66, 16, v175
	v_and_b32_e32 v67, 0xffff0000, v175
	v_mul_f32_e32 v4, v4, v64
	v_mul_f32_e32 v5, v5, v65
	v_mul_f32_e32 v6, v6, v66
	v_mul_f32_e32 v7, v7, v67
	v_cvt_pk_bf16_f32 v98, v4, v5
	v_cvt_pk_bf16_f32 v99, v6, v7
	v_mul_f32_e32 v8, v8, v69
	v_mul_f32_e32 v9, v9, v69
	v_mul_f32_e32 v10, v10, v69
	v_mul_f32_e32 v11, v11, v69
	v_mul_f32_e32 v8, v140, v8
	v_mul_f32_e32 v9, v141, v9
	v_mul_f32_e32 v10, v142, v10
	v_mul_f32_e32 v11, v143, v11
	v_lshlrev_b32_e32 v64, 16, v176
	v_and_b32_e32 v65, 0xffff0000, v176
	v_lshlrev_b32_e32 v66, 16, v177
	v_and_b32_e32 v67, 0xffff0000, v177
	v_mul_f32_e32 v8, v8, v64
	v_mul_f32_e32 v9, v9, v65
	v_mul_f32_e32 v10, v10, v66
	v_mul_f32_e32 v11, v11, v67
	v_cvt_pk_bf16_f32 v100, v8, v9
	v_cvt_pk_bf16_f32 v101, v10, v11
	v_mul_f32_e32 v12, v12, v69
	v_mul_f32_e32 v13, v13, v69
	v_mul_f32_e32 v14, v14, v69
	v_mul_f32_e32 v15, v15, v69
	v_mul_f32_e32 v12, v104, v12
	v_mul_f32_e32 v13, v105, v13
	v_mul_f32_e32 v14, v106, v14
	v_mul_f32_e32 v15, v107, v15
	v_lshlrev_b32_e32 v64, 16, v178
	v_and_b32_e32 v65, 0xffff0000, v178
	v_lshlrev_b32_e32 v66, 16, v179
	v_and_b32_e32 v67, 0xffff0000, v179
	v_mul_f32_e32 v12, v12, v64
	v_mul_f32_e32 v13, v13, v65
	v_mul_f32_e32 v14, v14, v66
	v_mul_f32_e32 v15, v15, v67
	v_cvt_pk_bf16_f32 v102, v12, v13
	v_cvt_pk_bf16_f32 v103, v14, v15
	s_nop 1
	v_permlane32_swap_b32_e32 v72, v74
	v_permlane32_swap_b32_e32 v73, v75
	v_permlane32_swap_b32_e32 v76, v78
	v_permlane32_swap_b32_e32 v77, v79
	v_permlane32_swap_b32_e32 v80, v82
	v_permlane32_swap_b32_e32 v81, v83
	v_permlane32_swap_b32_e32 v84, v86
	v_permlane32_swap_b32_e32 v85, v87
	v_permlane32_swap_b32_e32 v88, v90
	v_permlane32_swap_b32_e32 v89, v91
	v_permlane32_swap_b32_e32 v92, v94
	v_permlane32_swap_b32_e32 v93, v95
	v_permlane32_swap_b32_e32 v96, v98
	v_permlane32_swap_b32_e32 v97, v99
	v_permlane32_swap_b32_e32 v100, v102
	v_permlane32_swap_b32_e32 v101, v103
	global_store_dwordx4 v[110:111], v[72:75], off offset:0
	global_store_dwordx4 v[110:111], v[76:79], off offset:32
	global_store_dwordx4 v[110:111], v[80:83], off offset:64
	global_store_dwordx4 v[110:111], v[84:87], off offset:96
	global_store_dwordx4 v[110:111], v[88:91], off offset:128
	global_store_dwordx4 v[110:111], v[92:95], off offset:160
	global_store_dwordx4 v[110:111], v[96:99], off offset:192
	global_store_dwordx4 v[110:111], v[100:103], off offset:224
	s_branch .LBB0_302
